# best + GEMM prologues: k-tile-1 DMA group issued directly behind k-tile-0 (pipeline fills in one load latency)
# speedup vs baseline: 1.0032x; 1.0032x over previous
.LBB0_111:
	s_ashr_i32 s7, s2, 31
	s_mov_b64 s[64:65], 0x80
	v_writelane_b32 v255, s7, 49
	s_and_b32 s7, s5, 3
	s_add_i32 m0, s39, 0x18000
	v_lshl_add_u64 v[6:7], v[6:7], 0, s[64:65]
	s_ashr_i32 s45, s3, 31
	s_lshl_b32 s71, s4, 6
	s_lshl_b32 s14, s4, 13
	s_lshl_b32 s15, s7, 5
	s_lshl_b32 s16, s7, 12
	global_load_lds_dwordx4 v[6:7], off
	v_lshl_add_u64 v[4:5], v[4:5], 0, s[64:65]
	s_add_i32 m0, s39, 0x1a000
	s_add_i32 s92, s39, 0x8000
	s_add_i32 s93, s39, 0xa000
	global_load_lds_dwordx4 v[4:5], off
	v_lshl_add_u64 v[0:1], v[0:1], 0, s[64:65]
	s_mov_b32 m0, s92
	s_add_u32 s12, s10, 0x40080
	global_load_lds_dwordx4 v[0:1], off
	v_lshl_add_u64 v[0:1], v[2:3], 0, s[64:65]
	s_mov_b32 m0, s93
	s_addc_u32 s13, s11, 0
	global_load_lds_dwordx4 v[0:1], off
	s_add_i32 m0, s39, 0x1c000
	v_lshl_add_u64 v[0:1], s[12:13], 0, v[132:133]
	global_load_lds_dwordx4 v[0:1], off
	v_lshl_add_u64 v[0:1], s[12:13], 0, v[136:137]
	s_add_i32 m0, s39, 0x1e000
	v_and_b32_e32 v129, 15, v216
	global_load_lds_dwordx4 v[0:1], off
	s_waitcnt vmcnt(8)
	s_barrier
	s_cmpk_lt_u32 s6, 0x100
	v_bfe_u32 v12, v216, 4, 2
	v_lshlrev_b32_e32 v17, 4, v129
	v_readlane_b32 s12, v255, 32
	s_cselect_b64 s[66:67], -1, 0
	s_lshl_b32 s4, s4, 2
	v_lshl_or_b32 v138, v12, 8, v17
	v_readlane_b32 s13, v255, 33
	s_or_b32 s86, s4, s7
	s_and_b32 s6, s5, 2
	v_lshl_add_u64 v[0:1], s[12:13], 0, v[138:139]
	s_lshl_b64 s[4:5], s[86:87], 13
	v_or_b32_e32 v2, s71, v129
	v_lshl_add_u64 v[140:141], v[0:1], 0, s[4:5]
	s_add_i32 s4, 0, 0x20000
	s_lshl_b32 s5, s7, 2
	v_lshlrev_b32_e32 v185, 5, v2
	s_add_i32 s7, s5, s4
	s_add_i32 s5, s5, 0
	v_add_u32_e32 v217, s7, v185
	s_add_i32 s7, s5, 0x20200
	v_lshlrev_b32_e32 v13, 3, v12
	v_add_u32_e32 v254, s7, v185
	s_add_i32 s7, s5, 0x20400
	v_lshlrev_b32_e32 v0, 8, v216
	v_and_or_b32 v2, s15, 32, v13
	v_add_u32_e32 v191, s7, v185
	s_add_i32 s7, s5, 0x20600
	v_and_b32_e32 v0, 0x38000, v0
	v_lshlrev_b32_e32 v1, 11, v10
	v_add_u32_e32 v195, s7, v185
	s_add_i32 s7, s5, 0x21000
	v_lshlrev_b32_e32 v138, 2, v2
	v_or3_b32 v0, v8, v0, v1
	v_add_u32_e32 v198, s7, v185
	s_add_i32 s7, s5, 0x21200
	v_lshl_add_u64 v[142:143], s[50:51], 0, v[138:139]
	v_lshl_add_u64 v[144:145], s[52:53], 0, v[138:139]
	v_add_u32_e32 v138, v0, v9
	v_lshlrev_b32_e32 v0, 4, v11
	v_lshlrev_b32_e32 v14, 4, v12
	v_lshlrev_b32_e32 v15, 6, v216
	s_movk_i32 s0, 0x3c0
	v_add_u32_e32 v199, s7, v185
	s_add_i32 s7, s5, 0x21400
	s_add_i32 s5, s5, 0x21600
	v_and_b32_e32 v0, 0x78000, v0
	v_and_or_b32 v15, v15, s0, v14
	v_and_b32_e32 v16, 32, v16
	v_lshl_or_b32 v3, v129, 6, v14
	s_mov_b64 s[12:13], 0x40080
	s_waitcnt vmcnt(6)
	v_add_u32_e32 v201, s5, v185
	s_lshl_b32 s5, s6, 2
	v_or3_b32 v0, v8, v0, v1
	v_bitop3_b32 v3, v3, s14, v16 bitop3:0xde
	v_bitop3_b32 v179, s16, v15, v16 bitop3:0xf6
	v_or_b32_e32 v181, s15, v13
	s_add_i32 s4, s4, s5
	v_lshl_add_u64 v[146:147], v[138:139], 0, s[12:13]
	v_add_u32_e32 v138, v0, v9
	s_add_i32 s94, 0, 0x10000
	s_add_i32 s95, 0, 0x14000
	v_mbcnt_lo_u32_b32 v0, -1, 0
	v_cmp_eq_u32_e64 s[0:1], 0, v12
	v_or_b32_e32 v183, 0xfffffa00, v181
	v_add_u32_e32 v200, s7, v185
	v_writelane_b32 v255, s4, 50
	v_lshl_add_u64 v[148:149], v[138:139], 0, s[12:13]
	v_mov_b64_e32 v[150:151], 0x590
	v_mov_b64_e32 v[152:153], 0x58f
	v_add_u32_e32 v202, s94, v179
	v_add_u32_e32 v203, s95, v179
	v_add_u32_e32 v204, 0, v3
	s_mov_b32 s68, 0x3c800000
	s_mov_b32 s88, 0x800000
	s_mov_b32 s70, 0x45800000
	s_mov_b32 s96, 0xbfb8aa3b
	v_mov_b32_e32 v205, 0x3b808081
	v_mov_b64_e32 v[154:155], 0x57f
	v_mbcnt_hi_u32_b32 v206, -1, v0
	s_mov_b32 s89, 0
	s_barrier
	s_branch .LBB0_114

.LBB0_407:
	s_ashr_i32 s8, s28, 4
	s_ashr_i32 s9, s8, 31
	s_lshl_b32 s5, s28, 12
	s_lshl_b64 s[8:9], s[8:9], 23
	s_add_u32 s8, s96, s8
	s_addc_u32 s9, s91, s9
	s_and_b32 s5, s5, 0xf000
	s_add_u32 s36, s8, s5
	s_mov_b64 s[14:15], 0x80
	s_addc_u32 s37, s9, 0
	s_and_b32 s16, s4, 3
	s_add_i32 m0, s29, 0x18000
	v_lshl_add_u64 v[8:9], v[8:9], 0, s[14:15]
	s_and_b32 s9, s61, 0xffff
	s_ashr_i32 s54, s3, 31
	s_lshl_b32 s12, s1, 13
	s_lshl_b32 s18, s16, 12
	global_load_lds_dwordx4 v[8:9], off
	v_lshl_add_u64 v[6:7], v[6:7], 0, s[14:15]
	s_add_i32 m0, s29, 0x1a000
	s_add_i32 s55, s29, 0x8000
	s_add_i32 s56, s29, 0xa000
	global_load_lds_dwordx4 v[6:7], off
	v_lshl_add_u64 v[4:5], v[4:5], 0, s[14:15]
	s_mov_b32 m0, s55
	s_add_u32 s4, s30, 0x80080
	global_load_lds_dwordx4 v[4:5], off
	v_lshl_add_u64 v[2:3], v[2:3], 0, s[14:15]
	s_mov_b32 m0, s56
	s_addc_u32 s5, s31, 0
	global_load_lds_dwordx4 v[2:3], off
	s_add_i32 m0, s29, 0x1c000
	v_lshl_add_u64 v[2:3], s[4:5], 0, v[198:199]
	global_load_lds_dwordx4 v[2:3], off
	v_lshl_add_u64 v[2:3], s[4:5], 0, v[202:203]
	s_add_i32 m0, s29, 0x1e000
	v_lshlrev_b32_e32 v0, 12, v0
	global_load_lds_dwordx4 v[2:3], off
	s_waitcnt vmcnt(8)
	s_barrier
	v_bfe_u32 v2, v216, 4, 2
	s_sext_i32_i8 s59, s0
	v_lshl_or_b32 v204, v10, 4, v0
	v_lshl_or_b32 v206, v11, 4, v0
	v_lshlrev_b32_e32 v5, 4, v2
	v_lshlrev_b32_e32 v0, 6, v216
	s_movk_i32 s0, 0x3c0
	v_and_b32_e32 v4, 15, v216
	v_and_or_b32 v6, v0, s0, v5
	v_lshlrev_b32_e32 v0, 2, v216
	v_and_b32_e32 v7, 32, v0
	v_lshlrev_b32_e32 v0, 4, v4
	v_readlane_b32 s4, v255, 32
	v_lshl_or_b32 v0, v2, 8, v0
	v_readlane_b32 s5, v255, 33
	s_lshl_b32 s0, s1, 2
	s_waitcnt vmcnt(6)
	s_mov_b32 s11, 0x20000
	v_lshl_add_u64 v[2:3], s[4:5], 0, v[0:1]
	v_lshl_or_b32 v0, v4, 6, v5
	v_bitop3_b32 v0, v0, s12, v7 bitop3:0xde
	s_or_b32 s12, s0, s16
	s_lshl_b64 s[4:5], s[12:13], 13
	v_lshl_add_u64 v[208:209], v[2:3], 0, s[4:5]
	v_lshlrev_b32_e32 v2, 11, v4
	s_lshl_b32 s0, s16, 6
	v_lshl_or_b32 v2, s1, 17, v2
	s_brev_b32 s10, -2
	s_mov_b32 s8, s60
	v_mov_b32_e32 v205, v1
	v_mov_b32_e32 v207, v1
	v_bitop3_b32 v217, s18, v6, v7 bitop3:0xf6
	v_or3_b32 v218, s0, v2, v5
	v_mov_b64_e32 v[210:211], 0x100
	v_mov_b64_e32 v[212:213], 0xff
	s_movk_i32 s57, 0x1000
	s_mov_b32 s16, 0x3b808081
	v_add_u32_e32 v219, 0, v0
	s_mov_b32 s58, 0
	s_barrier
	s_branch .LBB0_409

.LBB0_494:
	s_mov_b64 s[24:25], 0x80
	s_and_b32 s19, s0, 3
	s_add_i32 m0, s50, 0x18000
	v_lshl_add_u64 v[6:7], v[6:7], 0, s[24:25]
	s_ashr_i32 s54, s3, 31
	s_ashr_i32 s55, s2, 31
	s_and_b32 s9, s13, 0xffff
	s_lshl_b32 s20, s7, 13
	s_lshl_b32 s26, s19, 12
	global_load_lds_dwordx4 v[6:7], off
	v_lshl_add_u64 v[4:5], v[4:5], 0, s[24:25]
	s_add_i32 m0, s50, 0x1a000
	s_add_i32 s56, s50, 0x8000
	s_add_i32 s57, s50, 0xa000
	global_load_lds_dwordx4 v[4:5], off
	v_lshl_add_u64 v[0:1], v[0:1], 0, s[24:25]
	s_mov_b32 m0, s56
	s_add_u32 s0, s44, 0x40080
	global_load_lds_dwordx4 v[0:1], off
	v_lshl_add_u64 v[0:1], v[2:3], 0, s[24:25]
	s_mov_b32 m0, s57
	s_addc_u32 s1, s45, 0
	global_load_lds_dwordx4 v[0:1], off
	s_add_i32 m0, s50, 0x1c000
	v_lshl_add_u64 v[0:1], s[0:1], 0, v[178:179]
	global_load_lds_dwordx4 v[0:1], off
	v_lshl_add_u64 v[0:1], s[0:1], 0, v[182:183]
	s_add_i32 m0, s50, 0x1e000
	v_lshlrev_b32_e32 v4, 6, v216
	global_load_lds_dwordx4 v[0:1], off
	s_waitcnt vmcnt(8)
	s_barrier
	v_bfe_u32 v0, v216, 4, 2
	v_lshlrev_b32_e32 v3, 4, v0
	s_movk_i32 s0, 0x3c0
	v_lshlrev_b32_e32 v5, 2, v216
	v_and_or_b32 v4, v4, s0, v3
	v_and_b32_e32 v5, 32, v5
	s_cmpk_lt_u32 s6, 0x100
	v_and_b32_e32 v1, 15, v216
	v_bitop3_b32 v198, s26, v4, v5 bitop3:0xf6
	s_cselect_b64 s[26:27], -1, 0
	s_lshl_b32 s6, s19, 2
	v_lshlrev_b32_e32 v2, 3, v0
	v_cmp_eq_u32_e64 s[0:1], 0, v0
	v_lshl_or_b32 v197, s7, 6, v1
	v_lshl_or_b32 v0, v1, 6, v3
	s_add_i32 s6, s6, 0
	v_bitop3_b32 v3, v0, s20, v5 bitop3:0xde
	v_or_b32_e32 v0, 16, v197
	s_add_i32 s6, s6, 0x20000
	v_lshl_or_b32 v199, s19, 5, v2
	v_lshlrev_b32_e32 v201, 11, v0
	v_or_b32_e32 v2, 48, v197
	v_lshl_add_u32 v209, v0, 4, s6
	v_lshlrev_b32_e32 v0, 8, v216
	v_lshlrev_b32_e32 v203, 11, v2
	v_lshl_add_u32 v211, v2, 4, s6
	v_and_b32_e32 v0, 0x38000, v0
	v_lshlrev_b32_e32 v2, 11, v10
	v_or_b32_e32 v1, 32, v197
	v_or3_b32 v0, v8, v0, v2
	s_mov_b64 s[28:29], 0x40080
	v_lshlrev_b32_e32 v202, 11, v1
	v_lshl_add_u32 v210, v1, 4, s6
	v_add_u32_e32 v0, v0, v9
	v_mov_b32_e32 v1, v179
	v_lshl_add_u64 v[184:185], v[0:1], 0, s[28:29]
	v_lshlrev_b32_e32 v0, 4, v11
	v_and_b32_e32 v0, 0x78000, v0
	v_or3_b32 v0, v8, v0, v2
	s_waitcnt vmcnt(6)
	v_add_u32_e32 v0, v0, v9
	s_movk_i32 s4, 0x100
	v_add_u32_e32 v4, 0x80, v197
	v_add_u32_e32 v5, 0x90, v197
	v_add_u32_e32 v6, 0xa0, v197
	v_add_u32_e32 v7, 0xb0, v197
	v_lshl_add_u64 v[186:187], v[0:1], 0, s[28:29]
	s_add_i32 s58, 0, 0x10000
	s_add_i32 s59, 0, 0x14000
	v_mbcnt_lo_u32_b32 v0, -1, 0
	v_cmp_gt_u32_e64 s[4:5], s4, v216
	s_mov_b32 s11, 0x20000
	s_brev_b32 s10, -2
	s_mov_b32 s8, s12
	v_lshlrev_b32_e32 v200, 11, v197
	v_lshlrev_b32_e32 v204, 11, v4
	v_lshlrev_b32_e32 v205, 11, v5
	v_lshlrev_b32_e32 v206, 11, v6
	v_lshlrev_b32_e32 v207, 11, v7
	v_lshl_add_u32 v208, v197, 4, s6
	v_lshl_add_u32 v212, v4, 4, s6
	v_lshl_add_u32 v213, v5, 4, s6
	v_lshl_add_u32 v214, v6, 4, s6
	v_lshl_add_u32 v215, v7, 4, s6
	v_mov_b64_e32 v[188:189], 0x100
	v_mov_b64_e32 v[190:191], 0xff
	v_add_u32_e32 v217, s58, v198
	v_add_u32_e32 v218, s59, v198
	v_add_u32_e32 v219, 0, v3
	v_mbcnt_hi_u32_b32 v220, -1, v0
	s_mov_b32 s62, 0
	s_barrier
	s_branch .LBB0_497

.LBB0_589:
	v_readlane_b32 s22, v255, 32
	s_mov_b64 s[20:21], 0x80
	s_sext_i32_i8 s56, s0
	s_and_b32 s0, s4, 3
	v_readlane_b32 s23, v255, 33
	s_add_i32 m0, s35, 0x18000
	v_lshl_add_u64 v[6:7], v[6:7], 0, s[20:21]
	s_lshl_b32 s0, s0, 12
	s_ashr_i32 s48, s3, 31
	s_add_i32 s16, 0, 0x20000
	s_and_b32 s9, s23, 0xffff
	global_load_lds_dwordx4 v[6:7], off
	v_lshl_add_u64 v[4:5], v[4:5], 0, s[20:21]
	s_add_i32 m0, s35, 0x1a000
	s_add_i32 s49, s35, 0x8000
	s_add_i32 s50, s35, 0xa000
	global_load_lds_dwordx4 v[4:5], off
	v_lshl_add_u64 v[0:1], v[0:1], 0, s[20:21]
	s_mov_b32 m0, s49
	s_add_u32 s10, s38, 0x40080
	global_load_lds_dwordx4 v[0:1], off
	v_lshl_add_u64 v[0:1], v[2:3], 0, s[20:21]
	s_mov_b32 m0, s50
	s_addc_u32 s11, s39, 0
	global_load_lds_dwordx4 v[0:1], off
	s_add_i32 m0, s35, 0x1c000
	v_lshl_add_u64 v[0:1], s[10:11], 0, v[130:131]
	global_load_lds_dwordx4 v[0:1], off
	v_lshl_add_u64 v[0:1], s[10:11], 0, v[134:135]
	s_add_i32 m0, s35, 0x1e000
	v_and_b32_e32 v12, 48, v216
	global_load_lds_dwordx4 v[0:1], off
	s_waitcnt vmcnt(8)
	s_barrier
	v_and_b32_e32 v0, 15, v216
	v_lshl_or_b32 v4, s1, 6, v0
	v_lshlrev_b32_e32 v5, 2, v4
	v_lshlrev_b32_e32 v0, 6, v0
	v_and_b32_e32 v6, 32, v5
	v_lshlrev_b32_e32 v149, 7, v4
	v_bitop3_b32 v0, v0, v6, v12 bitop3:0x36
	s_movk_i32 s1, 0xe000
	v_lshlrev_b32_e32 v2, 2, v216
	v_and_or_b32 v6, v149, s1, v0
	v_or_b32_e32 v0, 16, v4
	v_lshlrev_b32_e32 v1, 6, v216
	s_movk_i32 s8, 0x3c0
	v_and_b32_e32 v3, 32, v2
	v_add_u32_e32 v153, s16, v2
	v_lshlrev_b32_e32 v155, 7, v0
	v_or_b32_e32 v2, 48, v4
	v_lshl_add_u32 v165, v0, 2, s16
	v_lshlrev_b32_e32 v0, 8, v216
	v_and_or_b32 v1, v1, s8, v12
	v_lshlrev_b32_e32 v159, 7, v2
	v_lshl_add_u32 v167, v2, 2, s16
	v_and_b32_e32 v0, 0x38000, v0
	v_lshlrev_b32_e32 v2, 11, v10
	v_bitop3_b32 v151, s0, v1, v3 bitop3:0xf6
	v_or_b32_e32 v1, 32, v4
	v_or3_b32 v0, v8, v0, v2
	s_mov_b64 s[24:25], 0x40080
	v_lshlrev_b32_e32 v157, 7, v1
	v_lshl_add_u32 v166, v1, 2, s16
	v_add_u32_e32 v0, v0, v9
	v_mov_b32_e32 v1, v131
	s_cmpk_lt_u32 s5, 0x100
	v_lshl_add_u64 v[136:137], v[0:1], 0, s[24:25]
	v_lshlrev_b32_e32 v0, 4, v11
	s_mov_b32 s8, s22
	s_cselect_b64 s[22:23], -1, 0
	s_lshl_b32 s5, s4, 6
	s_lshl_b32 s4, s4, 20
	v_and_b32_e32 v0, 0x78000, v0
	s_waitcnt vmcnt(6)
	s_and_b32 s4, s4, 0x200000
	s_and_b32 s5, s5, 64
	v_or3_b32 v0, v8, v0, v2
	s_movk_i32 s0, 0x100
	s_or_b32 s4, s4, s5
	v_add_u32_e32 v3, 0x80, v4
	v_add_u32_e32 v7, 0x90, v4
	v_add_u32_e32 v13, 0xa0, v4
	v_add_u32_e32 v4, 0xb0, v4
	v_add_u32_e32 v0, v0, v9
	s_add_i32 s51, 0, 0x10000
	s_add_i32 s52, 0, 0x14000
	v_cmp_gt_u32_e64 s[0:1], s0, v216
	s_mov_b32 s11, 0x20000
	s_brev_b32 s10, -2
	v_lshlrev_b32_e32 v160, 7, v3
	v_lshlrev_b32_e32 v161, 7, v7
	v_lshlrev_b32_e32 v162, 7, v13
	v_lshlrev_b32_e32 v163, 7, v4
	v_add_u32_e32 v164, s16, v5
	v_lshl_add_u32 v168, v3, 2, s16
	v_lshl_add_u32 v169, v7, 2, s16
	v_lshl_add_u32 v170, v13, 2, s16
	v_lshl_add_u32 v171, v4, 2, s16
	v_or_b32_e32 v172, s4, v12
	v_lshl_add_u64 v[138:139], v[0:1], 0, s[24:25]
	v_mov_b64_e32 v[140:141], 0x400
	v_mov_b64_e32 v[142:143], 0x3ff
	v_add_u32_e32 v173, s51, v151
	v_add_u32_e32 v174, s52, v151
	v_add_u32_e32 v175, 0, v6
	s_add_i32 s53, 0, 0x20400
	v_mov_b32_e32 v176, 0x358637bd
	s_mov_b32 s54, 0x800000
	s_mov_b32 s55, 0
	s_barrier
	s_branch .LBB0_592

.LBB0_670:
	s_lshl_b32 s4, s4, 5
	s_and_b32 s8, s4, 0x60
	s_ashr_i32 s35, s3, 31
	s_lshl_b32 s6, s1, 13
	s_lshl_b32 s9, s8, 7
	s_add_u32 s4, s22, 0x20000
	s_addc_u32 s5, s23, 0
	s_add_i32 m0, s19, 0x18000
	v_lshl_add_u64 v[6:7], s[4:5], 0, v[128:129]
	global_load_lds_dwordx4 v[6:7], off
	s_add_i32 m0, s19, 0x1a000
	v_lshl_add_u64 v[6:7], s[4:5], 0, v[130:131]
	s_add_u32 s4, s20, 0x200000
	s_addc_u32 s5, s21, 0
	s_add_i32 s36, s19, 0x8000
	global_load_lds_dwordx4 v[6:7], off
	v_lshl_add_u64 v[6:7], s[4:5], 0, v[128:129]
	s_mov_b32 m0, s36
	s_add_i32 s37, s19, 0xa000
	global_load_lds_dwordx4 v[6:7], off
	v_lshl_add_u64 v[6:7], s[4:5], 0, v[130:131]
	s_add_u32 s4, s22, 0x24000
	s_mov_b32 m0, s37
	s_addc_u32 s5, s23, 0
	global_load_lds_dwordx4 v[6:7], off
	s_add_i32 m0, s19, 0x1c000
	v_lshl_add_u64 v[6:7], s[4:5], 0, v[128:129]
	global_load_lds_dwordx4 v[6:7], off
	v_lshl_add_u64 v[6:7], s[4:5], 0, v[130:131]
	s_add_i32 m0, s19, 0x1e000
	v_bfe_u32 v5, v216, 4, 2
	global_load_lds_dwordx4 v[6:7], off
	s_waitcnt vmcnt(8)
	s_barrier
	s_sext_i32_i8 s41, s0
	v_and_b32_e32 v6, 15, v216
	v_lshlrev_b32_e32 v7, 4, v5
	v_lshlrev_b32_e32 v8, 6, v216
	s_movk_i32 s0, 0x3c0
	v_lshlrev_b32_e32 v9, 2, v216
	v_and_or_b32 v8, v8, s0, v7
	v_and_b32_e32 v9, 32, v9
	v_lshl_or_b32 v190, s1, 6, v6
	v_lshl_or_b32 v6, v6, 6, v7
	s_waitcnt vmcnt(6)
	s_movk_i32 s0, 0x3800
	v_bitop3_b32 v6, v6, s6, v9 bitop3:0xde
	v_bitop3_b32 v191, s9, v8, v9 bitop3:0xf6
	v_and_or_b32 v2, v2, s0, v0
	v_add_u32_e32 v0, v0, v4
	s_add_i32 s38, 0, 0x10000
	s_add_i32 s39, 0, 0x14000
	v_lshl_or_b32 v192, v5, 2, s8
	v_add3_u32 v132, v2, v3, v1
	v_mov_b32_e32 v133, v129
	v_add3_u32 v134, v0, v3, v1
	v_mov_b32_e32 v135, v129
	v_mov_b64_e32 v[136:137], 0x100
	v_mov_b64_e32 v[138:139], 0xff
	v_add_u32_e32 v193, s38, v191
	v_add_u32_e32 v194, s39, v191
	v_add_u32_e32 v195, 0, v6
	s_mov_b32 s40, 0
	s_barrier
